# attention bounded loop: 32 scalar v_fma (scale, -mfix) paired into 16 v_pk_fma_f32
# speedup vs baseline: 1.0113x; 1.0028x over previous
.LBB0_291:
	s_add_u32 s26, s28, 0x4000
	s_addc_u32 s27, s29, 0
	s_and_b32 s0, s26, 0x4000
	s_add_i32 s0, s2, s0
	v_lshl_add_u64 v[48:49], v[96:97], 0, s[28:29]
	s_mov_b32 m0, s0
	s_waitcnt vmcnt(0)
	s_waitcnt lgkmcnt(0)
	s_barrier
	global_load_lds_dwordx4 v[48:49], off
	v_lshl_add_u64 v[48:49], v[94:95], 0, s[28:29]
	s_add_i32 m0, s0, 0x1000
	s_nop 0
	global_load_lds_dwordx4 v[48:49], off
	s_add_i32 m0, s0, 0x2000
	s_nop 0
	global_load_lds_dwordx4 v[92:93], off
	s_add_i32 m0, s0, 0x3000
	s_and_b32 s0, s28, 0x4000
	global_load_lds_dwordx4 v[90:91], off
	s_add_i32 s0, s60, s0
	v_add_u32_e32 v129, s0, v105
	v_add_u32_e32 v138, s0, v103
	ds_read_b128 v[48:51], v129
	ds_read_b128 v[52:55], v129 offset:2048
	ds_read_b128 v[56:59], v129 offset:4096
	ds_read_b128 v[60:63], v129 offset:6144
	ds_read_b128 v[64:67], v138
	ds_read_b128 v[68:71], v138 offset:2048
	ds_read_b128 v[72:75], v138 offset:4096
	ds_read_b128 v[76:79], v138 offset:6144
	s_waitcnt lgkmcnt(0)
	v_mfma_f32_16x16x32_bf16 v[80:83], v[48:51], v[36:39], 0
	v_mfma_f32_16x16x32_bf16 v[114:117], v[60:63], v[36:39], 0
	v_mfma_f32_16x16x32_bf16 v[60:63], v[60:63], v[44:47], 0
	v_mfma_f32_16x16x32_bf16 v[48:51], v[48:51], v[44:47], 0
	v_mfma_f32_16x16x32_bf16 v[106:109], v[52:55], v[36:39], 0
	v_mfma_f32_16x16x32_bf16 v[52:55], v[52:55], v[44:47], 0
	v_mfma_f32_16x16x32_bf16 v[110:113], v[56:59], v[36:39], 0
	v_mfma_f32_16x16x32_bf16 v[56:59], v[56:59], v[44:47], 0
	v_mfma_f32_16x16x32_bf16 v[118:121], v[64:67], v[32:35], v[80:83]
	v_mfma_f32_16x16x32_bf16 v[80:83], v[76:79], v[40:43], v[60:63]
	v_mfma_f32_16x16x32_bf16 v[122:125], v[64:67], v[40:43], v[48:51]
	v_mfma_f32_16x16x32_bf16 v[106:109], v[68:71], v[32:35], v[106:109]
	v_mfma_f32_16x16x32_bf16 v[130:133], v[68:71], v[40:43], v[52:55]
	v_mfma_f32_16x16x32_bf16 v[110:113], v[72:75], v[32:35], v[110:113]
	v_mfma_f32_16x16x32_bf16 v[134:137], v[72:75], v[40:43], v[56:59]
	v_mfma_f32_16x16x32_bf16 v[114:117], v[76:79], v[32:35], v[114:117]
	ds_read_b128 v[76:79], v129 offset:8192
	ds_read_b128 v[72:75], v129 offset:10240
	ds_read_b128 v[68:71], v129 offset:12288
	ds_read_b128 v[64:67], v129 offset:14336
	ds_read_b128 v[60:63], v138 offset:8192
	ds_read_b128 v[56:59], v138 offset:10240
	ds_read_b128 v[52:55], v138 offset:12288
	ds_read_b128 v[48:51], v138 offset:14336
	v_pk_fma_f32 v[118:119], v[118:119], s[76:77], v[128:129] op_sel_hi:[1,0,0] neg_lo:[0,0,1] neg_hi:[0,0,1]
	v_pk_fma_f32 v[120:121], v[120:121], s[76:77], v[128:129] op_sel_hi:[1,0,0] neg_lo:[0,0,1] neg_hi:[0,0,1]
	v_exp_f32_e32 v118, v118
	v_exp_f32_e32 v119, v119
	v_exp_f32_e32 v120, v120
	v_exp_f32_e32 v121, v121
	v_pk_fma_f32 v[106:107], v[106:107], s[76:77], v[128:129] op_sel_hi:[1,0,0] neg_lo:[0,0,1] neg_hi:[0,0,1]
	v_pk_fma_f32 v[108:109], v[108:109], s[76:77], v[128:129] op_sel_hi:[1,0,0] neg_lo:[0,0,1] neg_hi:[0,0,1]
	v_exp_f32_e32 v106, v106
	v_exp_f32_e32 v107, v107
	v_exp_f32_e32 v108, v108
	v_exp_f32_e32 v109, v109
	v_pk_add_f32 v[138:139], v[118:119], 0 op_sel_hi:[1,0]
	v_pk_add_f32 v[140:141], v[120:121], 0 op_sel_hi:[1,0]
	v_cvt_pk_bf16_f32 v118, v118, v119
	v_cvt_pk_bf16_f32 v119, v120, v121
	v_pk_add_f32 v[138:139], v[138:139], v[106:107]
	v_pk_add_f32 v[120:121], v[140:141], v[108:109]
	v_cvt_pk_bf16_f32 v106, v106, v107
	v_cvt_pk_bf16_f32 v107, v108, v109
	v_pk_fma_f32 v[108:109], v[110:111], s[76:77], v[128:129] op_sel_hi:[1,0,0] neg_lo:[0,0,1] neg_hi:[0,0,1]
	v_pk_fma_f32 v[110:111], v[112:113], s[76:77], v[128:129] op_sel_hi:[1,0,0] neg_lo:[0,0,1] neg_hi:[0,0,1]
	v_exp_f32_e32 v108, v108
	v_exp_f32_e32 v109, v109
	v_exp_f32_e32 v110, v110
	v_exp_f32_e32 v111, v111
	v_pk_add_f32 v[112:113], v[138:139], v[108:109]
	v_cvt_pk_bf16_f32 v108, v108, v109
	v_pk_add_f32 v[120:121], v[120:121], v[110:111]
	v_cvt_pk_bf16_f32 v109, v110, v111
	v_pk_fma_f32 v[110:111], v[114:115], s[76:77], v[128:129] op_sel_hi:[1,0,0] neg_lo:[0,0,1] neg_hi:[0,0,1]
	v_pk_fma_f32 v[114:115], v[116:117], s[76:77], v[128:129] op_sel_hi:[1,0,0] neg_lo:[0,0,1] neg_hi:[0,0,1]
	v_exp_f32_e32 v110, v110
	v_exp_f32_e32 v111, v111
	v_exp_f32_e32 v114, v114
	v_exp_f32_e32 v115, v115
	v_pk_fma_f32 v[80:81], v[80:81], s[76:77], v[128:129] op_sel_hi:[1,0,0] neg_lo:[0,0,1] neg_hi:[0,0,1]
	v_pk_add_f32 v[112:113], v[112:113], v[110:111]
	v_cvt_pk_bf16_f32 v110, v110, v111
	v_pk_add_f32 v[116:117], v[120:121], v[114:115]
	v_cvt_pk_bf16_f32 v111, v114, v115
	v_pk_mov_b32 v[114:115], v[112:113], v[116:117] op_sel:[1,0]
	v_mov_b32_e32 v113, v117
	v_pk_add_f32 v[112:113], v[114:115], v[112:113]
	v_pk_fma_f32 v[114:115], v[122:123], s[76:77], v[128:129] op_sel_hi:[1,0,0] neg_lo:[0,0,1] neg_hi:[0,0,1]
	v_exp_f32_e32 v114, v114
	v_exp_f32_e32 v115, v115
	v_pk_fma_f32 v[116:117], v[124:125], s[76:77], v[128:129] op_sel_hi:[1,0,0] neg_lo:[0,0,1] neg_hi:[0,0,1]
	v_exp_f32_e32 v116, v116
	v_exp_f32_e32 v117, v117
	v_pk_add_f32 v[120:121], v[114:115], 0 op_sel_hi:[1,0]
	v_cvt_pk_bf16_f32 v114, v114, v115
	v_cvt_pk_bf16_f32 v115, v116, v117
	ds_write2st64_b64 v102, v[118:119], v[114:115] offset0:64 offset1:68
	v_pk_fma_f32 v[114:115], v[130:131], s[76:77], v[128:129] op_sel_hi:[1,0,0] neg_lo:[0,0,1] neg_hi:[0,0,1]
	v_exp_f32_e32 v114, v114
	v_exp_f32_e32 v115, v115
	v_pk_add_f32 v[122:123], v[116:117], 0 op_sel_hi:[1,0]
	v_pk_fma_f32 v[116:117], v[132:133], s[76:77], v[128:129] op_sel_hi:[1,0,0] neg_lo:[0,0,1] neg_hi:[0,0,1]
	v_exp_f32_e32 v116, v116
	v_exp_f32_e32 v117, v117
	v_pk_add_f32 v[120:121], v[120:121], v[114:115]
	v_cvt_pk_bf16_f32 v114, v114, v115
	v_cvt_pk_bf16_f32 v115, v116, v117
	ds_write2st64_b64 v101, v[106:107], v[114:115] offset0:64 offset1:68
	v_pk_fma_f32 v[106:107], v[134:135], s[76:77], v[128:129] op_sel_hi:[1,0,0] neg_lo:[0,0,1] neg_hi:[0,0,1]
	v_pk_fma_f32 v[114:115], v[136:137], s[76:77], v[128:129] op_sel_hi:[1,0,0] neg_lo:[0,0,1] neg_hi:[0,0,1]
	v_exp_f32_e32 v106, v106
	v_exp_f32_e32 v107, v107
	v_exp_f32_e32 v114, v114
	v_exp_f32_e32 v115, v115
	v_pk_fma_f32 v[82:83], v[82:83], s[76:77], v[128:129] op_sel_hi:[1,0,0] neg_lo:[0,0,1] neg_hi:[0,0,1]
	v_exp_f32_e32 v80, v80
	v_exp_f32_e32 v81, v81
	v_exp_f32_e32 v82, v82
	v_exp_f32_e32 v83, v83
	v_pk_add_f32 v[118:119], v[122:123], v[116:117]
	v_pk_add_f32 v[116:117], v[120:121], v[106:107]
	v_pk_add_f32 v[118:119], v[118:119], v[114:115]
	v_cvt_pk_bf16_f32 v106, v106, v107
	v_cvt_pk_bf16_f32 v107, v114, v115
	ds_write2st64_b64 v100, v[108:109], v[106:107] offset0:64 offset1:68
	v_pk_add_f32 v[106:107], v[118:119], v[82:83]
	v_pk_add_f32 v[108:109], v[116:117], v[80:81]
	v_cvt_pk_bf16_f32 v80, v80, v81
	v_cvt_pk_bf16_f32 v81, v82, v83
	ds_write2st64_b64 v99, v[110:111], v[80:81] offset0:64 offset1:68
	v_pk_mov_b32 v[80:81], v[108:109], v[106:107] op_sel:[1,0]
	v_mov_b32_e32 v109, v107
	v_pk_add_f32 v[80:81], v[80:81], v[108:109]
	v_mov_b32_e32 v82, v112
	v_mov_b32_e32 v83, v80
	v_mov_b32_e32 v80, v113
	v_pk_add_f32 v[80:81], v[82:83], v[80:81]
	s_nop 0
	v_pk_add_f32 v[88:89], v[88:89], v[80:81]
	v_add_u32_e32 v80, v104, v105
	v_add_u32_e32 v81, v104, v103
	ds_read_b128 v[106:109], v80 offset:32768
	ds_read_b128 v[110:113], v80 offset:34816
	ds_read_b128 v[114:117], v81 offset:32768
	ds_read_b128 v[118:121], v81 offset:34816
	s_waitcnt lgkmcnt(0)
	v_mfma_f32_16x16x32_bf16 v[28:31], v[76:79], v[106:109], v[28:31]
	v_mfma_f32_16x16x32_bf16 v[16:19], v[76:79], v[110:113], v[16:19]
	v_mfma_f32_16x16x32_bf16 v[24:27], v[72:75], v[106:109], v[24:27]
	v_mfma_f32_16x16x32_bf16 v[8:11], v[72:75], v[110:113], v[8:11]
	v_mfma_f32_16x16x32_bf16 v[20:23], v[68:71], v[106:109], v[20:23]
	v_mfma_f32_16x16x32_bf16 v[4:7], v[68:71], v[110:113], v[4:7]
	v_mfma_f32_16x16x32_bf16 v[12:15], v[64:67], v[106:109], v[12:15]
	v_mfma_f32_16x16x32_bf16 v[0:3], v[64:67], v[110:113], v[0:3]
	v_mfma_f32_16x16x32_bf16 v[28:31], v[60:63], v[114:117], v[28:31]
	v_mfma_f32_16x16x32_bf16 v[16:19], v[60:63], v[118:121], v[16:19]
	v_mfma_f32_16x16x32_bf16 v[24:27], v[56:59], v[114:117], v[24:27]
	v_mfma_f32_16x16x32_bf16 v[8:11], v[56:59], v[118:121], v[8:11]
	v_mfma_f32_16x16x32_bf16 v[20:23], v[52:55], v[114:117], v[20:23]
	v_mfma_f32_16x16x32_bf16 v[4:7], v[52:55], v[118:121], v[4:7]
	v_mfma_f32_16x16x32_bf16 v[12:15], v[48:51], v[114:117], v[12:15]
	v_mfma_f32_16x16x32_bf16 v[0:3], v[48:51], v[118:121], v[0:3]
	v_lshl_add_u64 v[90:91], v[90:91], 0, s[10:11]
	v_lshl_add_u64 v[92:93], v[92:93], 0, s[10:11]
	s_cmp_lg_u32 s26, 0xfc000
	s_mov_b64 s[28:29], s[26:27]
	s_cbranch_scc1 .LBB0_291
	s_waitcnt vmcnt(0)
	s_waitcnt vmcnt(0)
	s_barrier
	v_add_u32_e32 v82, s60, v105
	v_add_u32_e32 v83, s60, v103
	ds_read_b128 v[48:51], v82 offset:16384
	ds_read_b128 v[52:55], v82 offset:18432
	ds_read_b128 v[56:59], v82 offset:20480
	ds_read_b128 v[60:63], v82 offset:22528
	ds_read_b128 v[64:67], v83 offset:16384
	ds_read_b128 v[68:71], v83 offset:18432
	ds_read_b128 v[72:75], v83 offset:20480
	ds_read_b128 v[76:79], v83 offset:22528
	s_waitcnt lgkmcnt(7)
	v_mfma_f32_16x16x32_bf16 v[90:93], v[48:51], v[36:39], 0
	v_mfma_f32_16x16x32_bf16 v[48:51], v[48:51], v[44:47], 0
	s_waitcnt lgkmcnt(6)
	v_mfma_f32_16x16x32_bf16 v[94:97], v[52:55], v[36:39], 0
	v_mfma_f32_16x16x32_bf16 v[52:55], v[52:55], v[44:47], 0
	s_waitcnt lgkmcnt(5)
	v_mfma_f32_16x16x32_bf16 v[104:107], v[56:59], v[36:39], 0
	v_mfma_f32_16x16x32_bf16 v[56:59], v[56:59], v[44:47], 0
	s_waitcnt lgkmcnt(4)
	v_mfma_f32_16x16x32_bf16 v[36:39], v[60:63], v[36:39], 0
	v_mfma_f32_16x16x32_bf16 v[44:47], v[60:63], v[44:47], 0
	s_waitcnt lgkmcnt(3)
	v_mfma_f32_16x16x32_bf16 v[90:93], v[64:67], v[32:35], v[90:93]
	v_mfma_f32_16x16x32_bf16 v[108:111], v[64:67], v[40:43], v[48:51]
	s_waitcnt lgkmcnt(2)
	v_mfma_f32_16x16x32_bf16 v[94:97], v[68:71], v[32:35], v[94:97]
	v_mfma_f32_16x16x32_bf16 v[68:71], v[68:71], v[40:43], v[52:55]
	s_waitcnt lgkmcnt(1)
	v_mfma_f32_16x16x32_bf16 v[104:107], v[72:75], v[32:35], v[104:107]
	v_mfma_f32_16x16x32_bf16 v[72:75], v[72:75], v[40:43], v[56:59]
	s_waitcnt lgkmcnt(0)
	v_mfma_f32_16x16x32_bf16 v[112:115], v[76:79], v[32:35], v[36:39]
	v_mfma_f32_16x16x32_bf16 v[64:67], v[76:79], v[40:43], v[44:47]
	ds_read_b128 v[60:63], v82 offset:24576
	ds_read_b128 v[56:59], v82 offset:26624
	ds_read_b128 v[52:55], v82 offset:28672
	ds_read_b128 v[48:51], v82 offset:30720
	ds_read_b128 v[44:47], v83 offset:24576
	ds_read_b128 v[40:43], v83 offset:26624
	ds_read_b128 v[36:39], v83 offset:28672
	ds_read_b128 v[32:35], v83 offset:30720
	v_fma_f32 v76, v90, s76, -v128
	v_fma_f32 v77, v91, s76, -v128
	v_fma_f32 v78, v92, s76, -v128
	v_fma_f32 v79, v93, s76, -v128
	v_exp_f32_e32 v76, v76
	v_exp_f32_e32 v77, v77
	v_exp_f32_e32 v78, v78
	v_exp_f32_e32 v79, v79
	v_fma_f32 v92, v96, s76, -v128
	v_pk_add_f32 v[82:83], v[76:77], 0 op_sel_hi:[1,0]
	v_cvt_pk_bf16_f32 v76, v76, v77
	v_pk_add_f32 v[90:91], v[78:79], 0 op_sel_hi:[1,0]
	v_cvt_pk_bf16_f32 v77, v78, v79
	v_fma_f32 v78, v94, s76, -v128
	v_fma_f32 v79, v95, s76, -v128
	v_fma_f32 v93, v97, s76, -v128
	v_exp_f32_e32 v78, v78
	v_exp_f32_e32 v79, v79
	v_exp_f32_e32 v92, v92
	v_exp_f32_e32 v93, v93
	v_fma_f32 v94, v106, s76, -v128
	v_pk_add_f32 v[82:83], v[82:83], v[78:79]
	v_cvt_pk_bf16_f32 v78, v78, v79
	v_pk_add_f32 v[90:91], v[90:91], v[92:93]
	v_cvt_pk_bf16_f32 v79, v92, v93
	v_fma_f32 v92, v104, s76, -v128
	v_fma_f32 v93, v105, s76, -v128
	v_fma_f32 v95, v107, s76, -v128
	v_exp_f32_e32 v92, v92
	v_exp_f32_e32 v93, v93
	v_exp_f32_e32 v94, v94
	v_exp_f32_e32 v95, v95
	v_fma_f32 v96, v114, s76, -v128
	v_pk_add_f32 v[82:83], v[82:83], v[92:93]
	v_cvt_pk_bf16_f32 v92, v92, v93
	v_pk_add_f32 v[90:91], v[90:91], v[94:95]
	v_cvt_pk_bf16_f32 v93, v94, v95
	v_fma_f32 v94, v112, s76, -v128
	v_fma_f32 v95, v113, s76, -v128
	v_fma_f32 v97, v115, s76, -v128
	v_exp_f32_e32 v94, v94
	v_exp_f32_e32 v95, v95
	v_exp_f32_e32 v96, v96
	v_exp_f32_e32 v97, v97
	v_fma_f32 v68, v68, s76, -v128
	v_pk_add_f32 v[82:83], v[82:83], v[94:95]
	v_cvt_pk_bf16_f32 v94, v94, v95
	v_pk_add_f32 v[90:91], v[90:91], v[96:97]
	v_cvt_pk_bf16_f32 v95, v96, v97
	v_fma_f32 v69, v69, s76, -v128
	v_pk_mov_b32 v[96:97], v[82:83], v[90:91] op_sel:[1,0]
	v_mov_b32_e32 v83, v91
	v_pk_add_f32 v[82:83], v[96:97], v[82:83]
	v_fma_f32 v90, v110, s76, -v128
	v_add_f32_e32 v82, v82, v83
	v_add_f32_e32 v88, v88, v82
	v_fma_f32 v82, v108, s76, -v128
	v_fma_f32 v83, v109, s76, -v128
	v_exp_f32_e32 v82, v82
	v_exp_f32_e32 v83, v83
	v_fma_f32 v91, v111, s76, -v128
	v_exp_f32_e32 v90, v90
	v_exp_f32_e32 v91, v91
	v_exp_f32_e32 v68, v68
	v_exp_f32_e32 v69, v69
	v_fma_f32 v70, v70, s76, -v128
	v_fma_f32 v71, v71, s76, -v128
	v_exp_f32_e32 v70, v70
	v_exp_f32_e32 v71, v71
	v_pk_add_f32 v[96:97], v[82:83], 0 op_sel_hi:[1,0]
	v_cvt_pk_bf16_f32 v82, v82, v83
	v_cvt_pk_bf16_f32 v83, v90, v91
	v_pk_add_f32 v[104:105], v[90:91], 0 op_sel_hi:[1,0]
	ds_write2st64_b64 v102, v[76:77], v[82:83] offset0:64 offset1:68
	v_pk_add_f32 v[82:83], v[96:97], v[68:69]
	v_cvt_pk_bf16_f32 v68, v68, v69
	v_cvt_pk_bf16_f32 v69, v70, v71
	v_pk_add_f32 v[76:77], v[104:105], v[70:71]
	ds_write2st64_b64 v101, v[78:79], v[68:69] offset0:64 offset1:68
	v_fma_f32 v68, v72, s76, -v128
	v_fma_f32 v69, v73, s76, -v128
	v_fma_f32 v70, v74, s76, -v128
	v_fma_f32 v71, v75, s76, -v128
	v_exp_f32_e32 v68, v68
	v_exp_f32_e32 v69, v69
	v_exp_f32_e32 v70, v70
	v_exp_f32_e32 v71, v71
	v_fma_f32 v64, v64, s76, -v128
	v_fma_f32 v65, v65, s76, -v128
	v_fma_f32 v66, v66, s76, -v128
	v_fma_f32 v67, v67, s76, -v128
	v_exp_f32_e32 v64, v64
	v_exp_f32_e32 v65, v65
	v_exp_f32_e32 v66, v66
	v_exp_f32_e32 v67, v67
	v_pk_add_f32 v[72:73], v[82:83], v[68:69]
	v_pk_add_f32 v[74:75], v[76:77], v[70:71]
	v_cvt_pk_bf16_f32 v68, v68, v69
	v_cvt_pk_bf16_f32 v69, v70, v71
	ds_write2st64_b64 v100, v[92:93], v[68:69] offset0:64 offset1:68
	v_pk_add_f32 v[68:69], v[74:75], v[66:67]
	v_pk_add_f32 v[70:71], v[72:73], v[64:65]
	v_cvt_pk_bf16_f32 v64, v64, v65
	v_cvt_pk_bf16_f32 v65, v66, v67
	ds_write2st64_b64 v99, v[94:95], v[64:65] offset0:64 offset1:68
	v_pk_mov_b32 v[64:65], v[70:71], v[68:69] op_sel:[1,0]
	v_mov_b32_e32 v71, v69
	v_pk_add_f32 v[64:65], v[64:65], v[70:71]
	s_nop 0
	v_add_f32_e32 v64, v64, v65
	v_add_f32_e32 v82, v89, v64
	ds_read_b128 v[64:67], v80 offset:32768
	ds_read_b128 v[68:71], v80 offset:34816
	ds_read_b128 v[72:75], v81 offset:32768
	ds_read_b128 v[76:79], v81 offset:34816
	s_waitcnt lgkmcnt(3)
	v_mfma_f32_16x16x32_bf16 v[28:31], v[60:63], v[64:67], v[28:31]
	s_waitcnt lgkmcnt(2)
	v_mfma_f32_16x16x32_bf16 v[16:19], v[60:63], v[68:71], v[16:19]
	v_mfma_f32_16x16x32_bf16 v[24:27], v[56:59], v[64:67], v[24:27]
	v_mfma_f32_16x16x32_bf16 v[8:11], v[56:59], v[68:71], v[8:11]
	v_mfma_f32_16x16x32_bf16 v[20:23], v[52:55], v[64:67], v[20:23]
	v_mfma_f32_16x16x32_bf16 v[4:7], v[52:55], v[68:71], v[4:7]
	v_mfma_f32_16x16x32_bf16 v[12:15], v[48:51], v[64:67], v[12:15]
	v_mfma_f32_16x16x32_bf16 v[0:3], v[48:51], v[68:71], v[0:3]
	s_waitcnt lgkmcnt(1)
	v_mfma_f32_16x16x32_bf16 v[28:31], v[44:47], v[72:75], v[28:31]
	s_waitcnt lgkmcnt(0)
	v_mfma_f32_16x16x32_bf16 v[16:19], v[44:47], v[76:79], v[16:19]
	v_mfma_f32_16x16x32_bf16 v[24:27], v[40:43], v[72:75], v[24:27]
	v_mfma_f32_16x16x32_bf16 v[8:11], v[40:43], v[76:79], v[8:11]
	v_mfma_f32_16x16x32_bf16 v[20:23], v[36:39], v[72:75], v[20:23]
	v_mfma_f32_16x16x32_bf16 v[4:7], v[36:39], v[76:79], v[4:7]
	v_mfma_f32_16x16x32_bf16 v[12:15], v[32:35], v[72:75], v[12:15]
	v_mfma_f32_16x16x32_bf16 v[32:35], v[32:35], v[76:79], v[0:3]
	s_nop 2
	ds_bpermute_b32 v0, v127, v88
	v_lshlrev_b32_e32 v144, 3, v98
	s_waitcnt lgkmcnt(0)
	v_add_f32_e32 v2, v88, v0
	ds_bpermute_b32 v3, v126, v2
	v_lshl_add_u64 v[0:1], s[24:25], 0, v[144:145]
	s_waitcnt lgkmcnt(0)
	v_add_f32_e32 v36, v2, v3
	v_div_scale_f32 v37, s[2:3], v36, v36, 1.0
	v_rcp_f32_e32 v38, v37
	v_div_scale_f32 v39, vcc, 1.0, v36, 1.0
	v_lshl_add_u64 v[2:3], v[0:1], 0, v[86:87]
	v_fma_f32 v40, -v37, v38, 1.0
	v_fmac_f32_e32 v38, v40, v38
	v_mul_f32_e32 v40, v39, v38
	v_fma_f32 v41, -v37, v40, v39
	v_fmac_f32_e32 v40, v41, v38
	v_fma_f32 v37, -v37, v40, v39
	v_div_fmas_f32 v37, v37, v38, v40
	v_div_fixup_f32 v36, v37, v36, 1.0
	v_pk_mul_f32 v[26:27], v[26:27], v[36:37] op_sel_hi:[1,0]
	v_pk_mul_f32 v[24:25], v[24:25], v[36:37] op_sel_hi:[1,0]
	v_pk_mul_f32 v[20:21], v[20:21], v[36:37] op_sel_hi:[1,0]
	v_cvt_pk_bf16_f32 v24, v24, v25
	v_cvt_pk_bf16_f32 v25, v26, v27
	ds_bpermute_b32 v26, v127, v82
	flat_store_dwordx2 v[2:3], v[24:25] offset:32
	v_cvt_pk_bf16_f32 v20, v20, v21
	v_pk_mul_f32 v[22:23], v[22:23], v[36:37] op_sel_hi:[1,0]
	v_pk_mul_f32 v[28:29], v[28:29], v[36:37] op_sel_hi:[1,0]
	s_waitcnt lgkmcnt(0)
	v_add_f32_e32 v24, v82, v26
	ds_bpermute_b32 v25, v126, v24
	v_cvt_pk_bf16_f32 v21, v22, v23
	flat_store_dwordx2 v[2:3], v[20:21] offset:64
	v_pk_mul_f32 v[12:13], v[12:13], v[36:37] op_sel_hi:[1,0]
	v_pk_mul_f32 v[30:31], v[30:31], v[36:37] op_sel_hi:[1,0]
	s_waitcnt lgkmcnt(0)
	v_add_f32_e32 v20, v24, v25
	v_div_scale_f32 v21, s[2:3], v20, v20, 1.0
	v_rcp_f32_e32 v22, v21
	v_cvt_pk_bf16_f32 v28, v28, v29
	v_cvt_pk_bf16_f32 v29, v30, v31
	flat_store_dwordx2 v[2:3], v[28:29]
	v_pk_mul_f32 v[14:15], v[14:15], v[36:37] op_sel_hi:[1,0]
	v_cvt_pk_bf16_f32 v12, v12, v13
	v_lshl_add_u64 v[0:1], v[0:1], 0, v[84:85]
	v_cvt_pk_bf16_f32 v13, v14, v15
	flat_store_dwordx2 v[2:3], v[12:13] offset:96
	v_fma_f32 v2, -v21, v22, 1.0
	v_fmac_f32_e32 v22, v2, v22
	v_div_scale_f32 v2, vcc, 1.0, v20, 1.0
	v_mul_f32_e32 v3, v2, v22
	v_fma_f32 v12, -v21, v3, v2
	v_fmac_f32_e32 v3, v12, v22
	v_fma_f32 v2, -v21, v3, v2
	v_div_fmas_f32 v2, v2, v22, v3
	v_div_fixup_f32 v2, v2, v20, 1.0
	v_pk_mul_f32 v[4:5], v[4:5], v[2:3] op_sel_hi:[1,0]
	v_pk_mul_f32 v[6:7], v[6:7], v[2:3] op_sel_hi:[1,0]
	v_cvt_pk_bf16_f32 v4, v4, v5
	v_pk_mul_f32 v[12:13], v[18:19], v[2:3] op_sel_hi:[1,0]
	v_cvt_pk_bf16_f32 v5, v6, v7
	v_pk_mul_f32 v[14:15], v[16:17], v[2:3] op_sel_hi:[1,0]
	v_pk_mul_f32 v[10:11], v[10:11], v[2:3] op_sel_hi:[1,0]
	v_pk_mul_f32 v[8:9], v[8:9], v[2:3] op_sel_hi:[1,0]
	flat_store_dwordx2 v[0:1], v[4:5] offset:64
	v_pk_mul_f32 v[4:5], v[34:35], v[2:3] op_sel_hi:[1,0]
	v_pk_mul_f32 v[2:3], v[32:33], v[2:3] op_sel_hi:[1,0]
	v_cvt_pk_bf16_f32 v14, v14, v15
	v_cvt_pk_bf16_f32 v15, v12, v13
	flat_store_dwordx2 v[0:1], v[14:15]
	v_cvt_pk_bf16_f32 v8, v8, v9
	v_cvt_pk_bf16_f32 v9, v10, v11
	flat_store_dwordx2 v[0:1], v[8:9] offset:32
	v_cvt_pk_bf16_f32 v2, v2, v3
	v_cvt_pk_bf16_f32 v3, v4, v5
	s_branch .LBB0_284
